# v086 + next-row prefetch in the fp6 table conversion loop
# speedup vs baseline: 1.0051x; 1.0051x over previous
.LBB0_130:
	v_mov_b32_e32 v16, v186
	v_readlane_b32 s4, v242, 0
	v_ashrrev_i32_e32 v17, 6, v16
	s_nop 0
	v_add_u32_e32 v17, s4, v17
	s_nop 0
	v_readfirstlane_b32 s10, v17
	s_cmpk_gt_i32 s10, 0x7fff
	s_cbranch_scc1 .LBB0_99
	s_load_dword s4, s[80:81], 0x10
	v_and_b32_e32 v17, 63, v16
	v_lshlrev_b32_e32 v16, 2, v17
	v_lshrrev_b32_e32 v36, 3, v17
	v_mul_u32_u24_e32 v36, 3, v36
	v_lshlrev_b32_e32 v36, 20, v36
	v_and_b32_e32 v37, 7, v17
	v_lshl_add_u32 v32, v37, 4, v36
	v_lshl_add_u32 v34, v37, 3, v36
	s_waitcnt lgkmcnt(0)
	s_lshr_b32 s4, s4, 16
	s_cmp_lg_u32 s4, 0
	s_cselect_b64 s[4:5], -1, 0
	s_cmp_lg_u64 s[4:5], 0
	s_addc_u32 s4, s78, 0
	s_lshl_b32 s11, s4, 3
	v_cmp_eq_u32_e64 s[4:5], 0, v17
	v_xor_b32_e32 v17, 1, v179
	v_cmp_lt_i32_e32 vcc, v17, v151
	v_mov_b32_e32 v33, v177
	v_mov_b32_e32 v35, v177
	v_cndmask_b32_e32 v17, v179, v17, vcc
	v_lshlrev_b32_e32 v36, 2, v17
	v_xor_b32_e32 v17, 2, v179
	v_cmp_lt_i32_e32 vcc, v17, v151
	v_lshlrev_b32_e32 v176, 2, v16
	s_nop 0
	v_cndmask_b32_e32 v17, v179, v17, vcc
	v_lshlrev_b32_e32 v37, 2, v17
	v_xor_b32_e32 v17, 4, v179
	v_cmp_lt_i32_e32 vcc, v17, v151
	s_nop 1
	v_cndmask_b32_e32 v17, v179, v17, vcc
	v_lshlrev_b32_e32 v38, 2, v17
	v_xor_b32_e32 v17, 8, v179
	v_cmp_lt_i32_e32 vcc, v17, v151
	s_nop 1
	v_cndmask_b32_e32 v17, v179, v17, vcc
	v_lshlrev_b32_e32 v39, 2, v17
	v_xor_b32_e32 v17, 16, v179
	v_cmp_lt_i32_e32 vcc, v17, v151
	s_nop 1
	v_cndmask_b32_e32 v17, v179, v17, vcc
	v_lshlrev_b32_e32 v40, 2, v17
	s_mov_b32 s16, s10
	s_and_b32 s17, s16, 0x3fff
	s_lshl_b32 s17, s17, 13
	s_cmpk_gt_i32 s16, 0x3fff
	s_cselect_b32 s18, s66, s64
	s_cselect_b32 s19, s67, s65
	s_add_u32 s18, s18, s17
	s_addc_u32 s19, s19, 0
	s_add_u32 s20, s18, 0x1000
	s_addc_u32 s21, s19, 0
	global_load_dwordx4 v[96:99], v176, s[18:19]
	global_load_dwordx4 v[100:103], v176, s[18:19] offset:1024
	global_load_dwordx4 v[104:107], v176, s[18:19] offset:2048
	global_load_dwordx4 v[108:111], v176, s[18:19] offset:3072
	global_load_dwordx4 v[112:115], v176, s[20:21]
	global_load_dwordx4 v[116:119], v176, s[20:21] offset:1024
	global_load_dwordx4 v[120:123], v176, s[20:21] offset:2048
	global_load_dwordx4 v[124:127], v176, s[20:21] offset:3072
	s_waitcnt vmcnt(0)
	s_branch .Lf6_take

.Lf6_take:
	s_waitcnt vmcnt(2)
	v_mov_b64_e32 v[16:17], v[96:97]
	v_mov_b64_e32 v[18:19], v[98:99]
	v_mov_b64_e32 v[20:21], v[100:101]
	v_mov_b64_e32 v[22:23], v[102:103]
	v_mov_b64_e32 v[24:25], v[104:105]
	v_mov_b64_e32 v[26:27], v[106:107]
	v_mov_b64_e32 v[28:29], v[108:109]
	v_mov_b64_e32 v[30:31], v[110:111]
	v_mov_b64_e32 v[42:43], v[112:113]
	v_mov_b64_e32 v[44:45], v[114:115]
	v_mov_b64_e32 v[46:47], v[116:117]
	v_mov_b64_e32 v[48:49], v[118:119]
	v_mov_b64_e32 v[50:51], v[120:121]
	v_mov_b64_e32 v[52:53], v[122:123]
	v_mov_b64_e32 v[54:55], v[124:125]
	v_mov_b64_e32 v[56:57], v[126:127]
.LBB0_133:
	s_and_b32 s12, s10, 0x3fff
	s_lshl_b32 s13, s12, 13
	s_cmpk_gt_i32 s10, 0x3fff
	s_cselect_b64 s[6:7], -1, 0
	s_and_b64 s[8:9], s[6:7], exec
	s_cselect_b32 s14, s66, s64
	s_cselect_b32 s15, s67, s65
	s_cselect_b32 s8, s71, s69
	s_cselect_b32 s9, s70, s68
	s_add_u32 s14, s14, s13
	s_addc_u32 s15, s15, 0
	s_add_i32 s16, s10, s11
	s_cmp_lt_i32 s16, 0x8000
	s_cbranch_scc0 .Lf6_nopf
	s_and_b32 s17, s16, 0x3fff
	s_lshl_b32 s17, s17, 13
	s_cmpk_gt_i32 s16, 0x3fff
	s_cselect_b32 s18, s66, s64
	s_cselect_b32 s19, s67, s65
	s_add_u32 s18, s18, s17
	s_addc_u32 s19, s19, 0
	s_add_u32 s20, s18, 0x1000
	s_addc_u32 s21, s19, 0
	global_load_dwordx4 v[96:99], v176, s[18:19]
	global_load_dwordx4 v[100:103], v176, s[18:19] offset:1024
	global_load_dwordx4 v[104:107], v176, s[18:19] offset:2048
	global_load_dwordx4 v[108:111], v176, s[18:19] offset:3072
	global_load_dwordx4 v[112:115], v176, s[20:21]
	global_load_dwordx4 v[116:119], v176, s[20:21] offset:1024
	global_load_dwordx4 v[120:123], v176, s[20:21] offset:2048
	global_load_dwordx4 v[124:127], v176, s[20:21] offset:3072
.Lf6_nopf:
	s_mul_i32 s13, s12, 0xc0
	v_max_f32_e64 v41, |v19|, |v19|
	v_max_f32_e64 v58, |v18|, |v18|
	v_max_f32_e64 v59, |v23|, |v23|
	v_max_f32_e64 v60, |v22|, |v22|
	v_max_f32_e64 v61, |v27|, |v27|
	v_max_f32_e64 v62, |v26|, |v26|
	v_max_f32_e64 v63, |v31|, |v31|
	v_max_f32_e64 v64, |v30|, |v30|
	v_max_f32_e32 v41, v58, v41
	v_max_f32_e32 v58, v60, v59
	v_max_f32_e32 v59, v62, v61
	v_max_f32_e32 v60, v64, v63
	v_max3_f32 v41, |v16|, |v17|, v41
	v_max3_f32 v58, |v20|, |v21|, v58
	v_max_f32_e64 v61, |v45|, |v45|
	v_max_f32_e64 v62, |v44|, |v44|
	v_max_f32_e64 v63, |v49|, |v49|
	v_max_f32_e64 v64, |v48|, |v48|
	v_max3_f32 v59, |v24|, |v25|, v59
	v_max3_f32 v60, |v28|, |v29|, v60
	v_max_f32_e64 v65, |v53|, |v53|
	v_max_f32_e64 v66, |v52|, |v52|
	v_max_f32_e64 v67, |v57|, |v57|
	v_max_f32_e64 v68, |v56|, |v56|
	v_max3_f32 v41, v41, 0, v58
	v_max_f32_e32 v58, v62, v61
	v_max_f32_e32 v61, v64, v63
	v_max_f32_e32 v62, v66, v65
	v_max_f32_e32 v63, v68, v67
	v_max3_f32 v41, v41, v59, v60
	v_max3_f32 v58, |v42|, |v43|, v58
	v_max3_f32 v59, |v46|, |v47|, v61
	v_max3_f32 v60, |v50|, |v51|, v62
	v_max3_f32 v61, |v54|, |v55|, v63
	v_max3_f32 v41, v41, v58, v59
	v_max3_f32 v41, v41, v60, v61
	ds_bpermute_b32 v58, v36, v41
	v_mov_b32_e32 v59, v18
	v_pk_mov_b32 v[18:19], v[18:19], v[20:21] op_sel:[1,0]
	v_mov_b32_e32 v20, v21
	v_mov_b32_e32 v21, v22
	s_waitcnt lgkmcnt(0)
	v_max_f32_e32 v58, v58, v58
	v_max_f32_e32 v41, v41, v58
	ds_bpermute_b32 v60, v37, v41
	v_mov_b32_e32 v58, v17
	v_pk_mov_b32 v[22:23], v[22:23], v[24:25] op_sel:[1,0]
	v_mov_b32_e32 v24, v25
	s_waitcnt lgkmcnt(0)
	v_max_f32_e32 v17, v60, v60
	v_max_f32_e32 v17, v41, v17
	ds_bpermute_b32 v41, v38, v17
	s_waitcnt lgkmcnt(0)
	v_max_f32_e32 v25, v41, v41
	v_max_f32_e32 v17, v17, v25
	ds_bpermute_b32 v41, v39, v17
	v_mov_b32_e32 v25, v26
	v_pk_mov_b32 v[26:27], v[26:27], v[28:29] op_sel:[1,0]
	v_mov_b32_e32 v28, v29
	v_mov_b32_e32 v29, v30
	s_waitcnt lgkmcnt(0)
	v_max_f32_e32 v30, v41, v41
	v_max_f32_e32 v17, v17, v30
	ds_bpermute_b32 v41, v40, v17
	v_pk_mov_b32 v[30:31], v[30:31], v[42:43] op_sel:[1,0]
	v_mov_b32_e32 v42, v43
	v_mov_b32_e32 v43, v44
	v_pk_mov_b32 v[44:45], v[44:45], v[46:47] op_sel:[1,0]
	s_waitcnt lgkmcnt(0)
	v_max_f32_e32 v41, v41, v41
	v_max_f32_e32 v17, v17, v41
	ds_bpermute_b32 v41, v150, v17
	v_mov_b32_e32 v46, v47
	v_mov_b32_e32 v47, v48
	v_pk_mov_b32 v[48:49], v[48:49], v[50:51] op_sel:[1,0]
	v_mov_b32_e32 v50, v51
	s_waitcnt lgkmcnt(0)
	v_max_f32_e32 v41, v41, v41
	v_max_f32_e32 v41, v17, v41
	v_div_scale_f32 v17, s[14:15], v41, v41, s94
	v_rcp_f32_e32 v60, v17
	v_mov_b32_e32 v51, v52
	v_div_scale_f32 v52, vcc, s94, v41, s94
	v_fma_f32 v61, -v17, v60, 1.0
	v_fmac_f32_e32 v60, v61, v60
	v_mul_f32_e32 v61, v52, v60
	v_fma_f32 v62, -v17, v61, v52
	v_fmac_f32_e32 v61, v62, v60
	v_fma_f32 v17, -v17, v61, v52
	v_div_fmas_f32 v17, v17, v60, v61
	v_div_fixup_f32 v17, v17, v41, s94
	v_cmp_lt_f32_e32 vcc, 0, v41
	s_add_u32 s14, s9, s13
	s_addc_u32 s15, s8, 0
	v_cndmask_b32_e32 v52, 1.0, v17, vcc
	v_pk_mul_f32 v[18:19], v[18:19], v[52:53] op_sel_hi:[1,0]
	v_pk_mul_f32 v[20:21], v[20:21], v[52:53] op_sel_hi:[1,0]
	v_pk_mul_f32 v[24:25], v[24:25], v[52:53] op_sel_hi:[1,0]
	v_pk_mul_f32 v[30:31], v[30:31], v[52:53] op_sel_hi:[1,0]
	v_cvt_pk_f16_f32 v18, v18, v19
	v_cvt_pk_f16_f32 v19, v20, v21
	v_cvt_pk_f16_f32 v21, v24, v25
	v_cvt_pk_f16_f32 v24, v30, v31
	v_pk_mov_b32 v[30:31], v[52:53], v[54:55] op_sel:[1,0]
	v_pk_mul_f32 v[42:43], v[42:43], v[52:53] op_sel_hi:[1,0]
	v_pk_mul_f32 v[30:31], v[30:31], v[52:53] op_sel_hi:[1,0]
	v_cvt_pk_f16_f32 v25, v42, v43
	v_cvt_pk_f16_f32 v42, v30, v31
	v_mov_b32_e32 v30, v55
	v_mov_b32_e32 v31, v56
	v_pk_mul_f32 v[30:31], v[30:31], v[52:53] op_sel_hi:[1,0]
	v_fma_mixlo_f16 v60, v16, v52, 0
	v_pk_mul_f32 v[16:17], v[58:59], v[52:53] op_sel_hi:[1,0]
	v_pk_mul_f32 v[22:23], v[22:23], v[52:53] op_sel_hi:[1,0]
	v_pk_mul_f32 v[26:27], v[26:27], v[52:53] op_sel_hi:[1,0]
	v_pk_mul_f32 v[28:29], v[28:29], v[52:53] op_sel_hi:[1,0]
	v_pk_mul_f32 v[44:45], v[44:45], v[52:53] op_sel_hi:[1,0]
	v_pk_mul_f32 v[46:47], v[46:47], v[52:53] op_sel_hi:[1,0]
	v_pk_mul_f32 v[48:49], v[48:49], v[52:53] op_sel_hi:[1,0]
	v_pk_mul_f32 v[50:51], v[50:51], v[52:53] op_sel_hi:[1,0]
	v_cvt_pk_f16_f32 v31, v30, v31
	v_cvt_pk_f16_f32 v17, v16, v17
	v_cvt_pk_f16_f32 v20, v22, v23
	v_cvt_pk_f16_f32 v22, v26, v27
	v_cvt_pk_f16_f32 v23, v28, v29
	v_cvt_pk_f16_f32 v26, v44, v45
	v_cvt_pk_f16_f32 v27, v46, v47
	v_cvt_pk_f16_f32 v28, v48, v49
	v_cvt_pk_f16_f32 v29, v50, v51
	v_alignbit_b32 v30, v31, v42, 16
	v_lshrrev_b32_e32 v31, 16, v31
	v_pack_b32_f16 v16, v60, v17
	v_alignbit_b32 v17, v18, v17, 16
	v_alignbit_b32 v18, v19, v18, 16
	v_alignbit_b32 v19, v20, v19, 16
	v_alignbit_b32 v20, v21, v20, 16
	v_alignbit_b32 v21, v22, v21, 16
	v_alignbit_b32 v22, v23, v22, 16
	v_alignbit_b32 v23, v24, v23, 16
	v_alignbit_b32 v24, v25, v24, 16
	v_alignbit_b32 v25, v26, v25, 16
	v_alignbit_b32 v26, v27, v26, 16
	v_alignbit_b32 v27, v28, v27, 16
	v_alignbit_b32 v28, v29, v28, 16
	v_alignbit_b32 v29, v42, v29, 16
	v_fma_mixhi_f16 v31, v57, v52, 0
	v_cvt_scalef32_pk32_fp6_f16 v[42:47], v[16:31], 1.0
	v_lshl_add_u64 v[16:17], s[14:15], 0, v[32:33]
	global_store_dwordx4 v[16:17], v[42:45], off
	v_lshl_add_u64 v[16:17], s[14:15], 0, v[34:35]
	global_store_dwordx2 v[16:17], v[46:47], off offset:128
	s_and_saveexec_b64 s[8:9], s[4:5]
	s_cbranch_execz .LBB0_132
	s_and_b64 s[6:7], s[6:7], exec
	s_cselect_b32 s7, s59, s57
	s_cselect_b32 s6, s58, s56
	s_lshl_b32 s12, s12, 2
	v_mul_f32_e32 v16, 0x3e124925, v41
	v_cndmask_b32_e32 v16, 1.0, v16, vcc
	v_mov_b32_e32 v17, s12
	global_store_dword v17, v16, s[6:7]
	s_branch .LBB0_132
